# attention s-major PV pipelining, SSM load waits relaxed, next-unit atomic issued after the unit prologue barrier
# speedup vs baseline: 1.0520x; 1.0098x over previous
.LBB0_495:
	v_mfma_f32_32x32x16_bf16 v[50:65], v[34:37], v[78:81], 0
	v_mul_f32_e64 v120, v156, v114
	v_mul_f32_e64 v121, v157, v115
	v_mul_f32_e64 v114, v160, v114
	v_mul_f32_e64 v115, v161, v115
	v_fma_f32 v120, v160, v112, -v120
	v_fma_f32 v121, v161, v113, -v121
	v_pk_fma_f32 v[112:113], v[156:157], v[112:113], v[114:115]
	s_add_i32 s78, s78, 1
	v_lshl_add_u64 v[110:111], v[110:111], 0, s[70:71]
	s_cmp_eq_u32 s78, 16
	v_mfma_f32_32x32x16_bf16 v[2:17], v[34:37], v[66:69], 0
	s_nop 0
	v_mov_b32_e32 v116, v50
	v_mfma_f32_32x32x16_bf16 v[18:33], v[34:37], v[70:73], 0
	s_nop 8
	v_mov_b32_e32 v117, v2
	v_add_f32_e64 v116, v120, v116
	v_add_f32_e64 v117, v121, v117
	v_mov_b32_e32 v2, v51
	v_mfma_f32_32x32x16_bf16 v[34:49], v[34:37], v[74:77], 0
	v_mov_b32_e32 v118, v18
	v_mov_b32_e32 v50, v20
	v_mov_b32_e32 v20, v22
	s_nop 8
	v_mov_b32_e32 v119, v34
	v_pk_add_f32 v[112:113], v[112:113], v[118:119]
	v_mov_b32_e32 v34, v19
	v_pk_mul_f32 v[18:19], v[156:157], v[112:113]
	v_mov_b32_e32 v51, v36
	v_pk_fma_f32 v[18:19], v[160:161], v[116:117], v[18:19] neg_lo:[0,0,1] neg_hi:[0,0,1]
	v_mov_b32_e32 v36, v21
	v_pk_add_f32 v[2:3], v[2:3], v[18:19]
	v_pk_mul_f32 v[18:19], v[160:161], v[112:113]
	v_mov_b32_e32 v21, v38
	v_pk_fma_f32 v[18:19], v[156:157], v[116:117], v[18:19]
	v_mov_b32_e32 v38, v23
	v_pk_add_f32 v[18:19], v[34:35], v[18:19]
	v_mov_b32_e32 v34, v52
	v_pk_mul_f32 v[112:113], v[156:157], v[18:19]
	v_mov_b32_e32 v35, v4
	v_pk_fma_f32 v[112:113], v[160:161], v[2:3], v[112:113] neg_lo:[0,0,1] neg_hi:[0,0,1]
	v_pk_mul_f32 v[2:3], v[156:157], v[2:3]
	v_pk_add_f32 v[34:35], v[34:35], v[112:113]
	v_pk_fma_f32 v[2:3], v[160:161], v[18:19], v[2:3]
	v_mov_b32_e32 v4, v53
	v_pk_add_f32 v[2:3], v[50:51], v[2:3]
	s_nop 0
	v_pk_mul_f32 v[18:19], v[156:157], v[2:3]
	s_nop 0
	v_pk_fma_f32 v[18:19], v[160:161], v[34:35], v[18:19] neg_lo:[0,0,1] neg_hi:[0,0,1]
	s_nop 0
	v_pk_add_f32 v[4:5], v[4:5], v[18:19]
	v_pk_mul_f32 v[18:19], v[156:157], v[34:35]
	s_nop 0
	v_pk_fma_f32 v[2:3], v[160:161], v[2:3], v[18:19]
	v_mov_b32_e32 v18, v54
	v_pk_add_f32 v[2:3], v[36:37], v[2:3]
	v_mov_b32_e32 v19, v6
	v_pk_mul_f32 v[34:35], v[156:157], v[2:3]
	v_mov_b32_e32 v6, v55
	v_pk_fma_f32 v[34:35], v[160:161], v[4:5], v[34:35] neg_lo:[0,0,1] neg_hi:[0,0,1]
	v_pk_mul_f32 v[4:5], v[156:157], v[4:5]
	v_pk_add_f32 v[18:19], v[18:19], v[34:35]
	v_pk_fma_f32 v[2:3], v[160:161], v[2:3], v[4:5]
	s_waitcnt vmcnt(1)
	v_mov_b64_e32 v[34:35], v[86:87]
	v_pk_add_f32 v[2:3], v[20:21], v[2:3]
	v_mov_b64_e32 v[36:37], v[88:89]
	v_pk_mul_f32 v[4:5], v[156:157], v[2:3]
	v_mov_b64_e32 v[88:89], v[84:85]
	v_pk_fma_f32 v[4:5], v[160:161], v[18:19], v[4:5] neg_lo:[0,0,1] neg_hi:[0,0,1]
	v_mov_b64_e32 v[86:87], v[82:83]
	v_pk_add_f32 v[4:5], v[6:7], v[4:5]
	v_pk_mul_f32 v[6:7], v[156:157], v[18:19]
	v_mov_b32_e32 v18, v24
	v_pk_fma_f32 v[2:3], v[160:161], v[2:3], v[6:7]
	v_mov_b32_e32 v19, v40
	v_pk_add_f32 v[2:3], v[38:39], v[2:3]
	v_mov_b32_e32 v6, v56
	v_pk_mul_f32 v[20:21], v[156:157], v[2:3]
	v_mov_b32_e32 v7, v8
	v_pk_fma_f32 v[20:21], v[160:161], v[4:5], v[20:21] neg_lo:[0,0,1] neg_hi:[0,0,1]
	v_pk_mul_f32 v[4:5], v[156:157], v[4:5]
	v_pk_add_f32 v[6:7], v[6:7], v[20:21]
	v_pk_fma_f32 v[2:3], v[160:161], v[2:3], v[4:5]
	v_mov_b32_e32 v40, v25
	v_pk_add_f32 v[2:3], v[18:19], v[2:3]
	v_mov_b32_e32 v8, v57
	v_pk_mul_f32 v[4:5], v[156:157], v[2:3]
	v_mov_b64_e32 v[82:83], v[90:91]
	v_pk_fma_f32 v[4:5], v[160:161], v[6:7], v[4:5] neg_lo:[0,0,1] neg_hi:[0,0,1]
	v_pk_mul_f32 v[6:7], v[156:157], v[6:7]
	v_pk_add_f32 v[4:5], v[8:9], v[4:5]
	v_pk_fma_f32 v[2:3], v[160:161], v[2:3], v[6:7]
	v_mov_b32_e32 v8, v26
	v_pk_add_f32 v[2:3], v[40:41], v[2:3]
	v_mov_b32_e32 v9, v42
	v_pk_mul_f32 v[18:19], v[156:157], v[2:3]
	v_mov_b32_e32 v6, v58
	v_pk_fma_f32 v[18:19], v[160:161], v[4:5], v[18:19] neg_lo:[0,0,1] neg_hi:[0,0,1]
	v_pk_mul_f32 v[4:5], v[156:157], v[4:5]
	v_mov_b32_e32 v7, v10
	v_pk_fma_f32 v[2:3], v[160:161], v[2:3], v[4:5]
	v_pk_add_f32 v[6:7], v[6:7], v[18:19]
	v_pk_add_f32 v[2:3], v[8:9], v[2:3]
	v_mov_b32_e32 v42, v27
	v_pk_mul_f32 v[4:5], v[156:157], v[2:3]
	v_mov_b32_e32 v10, v59
	v_pk_fma_f32 v[4:5], v[160:161], v[6:7], v[4:5] neg_lo:[0,0,1] neg_hi:[0,0,1]
	v_pk_mul_f32 v[6:7], v[156:157], v[6:7]
	v_pk_add_f32 v[4:5], v[10:11], v[4:5]
	v_pk_fma_f32 v[2:3], v[160:161], v[2:3], v[6:7]
	v_mov_b32_e32 v8, v28
	v_pk_add_f32 v[2:3], v[42:43], v[2:3]
	v_mov_b32_e32 v9, v44
	v_pk_mul_f32 v[10:11], v[156:157], v[2:3]
	v_mov_b32_e32 v6, v60
	v_pk_fma_f32 v[10:11], v[160:161], v[4:5], v[10:11] neg_lo:[0,0,1] neg_hi:[0,0,1]
	v_pk_mul_f32 v[4:5], v[156:157], v[4:5]
	v_mov_b32_e32 v7, v12
	v_pk_fma_f32 v[2:3], v[160:161], v[2:3], v[4:5]
	v_pk_add_f32 v[6:7], v[6:7], v[10:11]
	v_pk_add_f32 v[2:3], v[8:9], v[2:3]
	v_mov_b32_e32 v44, v29
	v_pk_mul_f32 v[4:5], v[156:157], v[2:3]
	v_mov_b32_e32 v12, v61
	v_pk_fma_f32 v[4:5], v[160:161], v[6:7], v[4:5] neg_lo:[0,0,1] neg_hi:[0,0,1]
	v_pk_mul_f32 v[6:7], v[156:157], v[6:7]
	v_pk_add_f32 v[4:5], v[12:13], v[4:5]
	v_pk_fma_f32 v[2:3], v[160:161], v[2:3], v[6:7]
	v_mov_b32_e32 v8, v30
	v_pk_add_f32 v[2:3], v[44:45], v[2:3]
	v_mov_b32_e32 v9, v46
	v_pk_mul_f32 v[10:11], v[156:157], v[2:3]
	v_mov_b32_e32 v6, v62
	v_pk_fma_f32 v[10:11], v[160:161], v[4:5], v[10:11] neg_lo:[0,0,1] neg_hi:[0,0,1]
	v_pk_mul_f32 v[4:5], v[156:157], v[4:5]
	v_mov_b32_e32 v7, v14
	v_pk_fma_f32 v[2:3], v[160:161], v[2:3], v[4:5]
	v_pk_add_f32 v[6:7], v[6:7], v[10:11]
	v_pk_add_f32 v[2:3], v[8:9], v[2:3]
	v_mov_b32_e32 v46, v31
	v_pk_mul_f32 v[4:5], v[156:157], v[2:3]
	v_mov_b32_e32 v14, v63
	v_pk_fma_f32 v[4:5], v[160:161], v[6:7], v[4:5] neg_lo:[0,0,1] neg_hi:[0,0,1]
	v_pk_mul_f32 v[6:7], v[156:157], v[6:7]
	v_pk_add_f32 v[4:5], v[14:15], v[4:5]
	v_pk_fma_f32 v[2:3], v[160:161], v[2:3], v[6:7]
	v_mov_b32_e32 v8, v32
	v_pk_add_f32 v[2:3], v[46:47], v[2:3]
	v_mov_b32_e32 v9, v48
	v_pk_mul_f32 v[10:11], v[156:157], v[2:3]
	v_mov_b32_e32 v6, v64
	v_pk_fma_f32 v[10:11], v[160:161], v[4:5], v[10:11] neg_lo:[0,0,1] neg_hi:[0,0,1]
	v_pk_mul_f32 v[4:5], v[156:157], v[4:5]
	v_mov_b32_e32 v7, v16
	v_pk_fma_f32 v[2:3], v[160:161], v[2:3], v[4:5]
	v_pk_add_f32 v[6:7], v[6:7], v[10:11]
	v_pk_add_f32 v[2:3], v[8:9], v[2:3]
	v_mov_b32_e32 v16, v65
	v_pk_mul_f32 v[4:5], v[156:157], v[2:3]
	v_mov_b32_e32 v48, v33
	v_pk_fma_f32 v[4:5], v[160:161], v[6:7], v[4:5] neg_lo:[0,0,1] neg_hi:[0,0,1]
	v_mov_b64_e32 v[84:85], v[92:93]
	v_pk_add_f32 v[112:113], v[16:17], v[4:5]
	v_pk_mul_f32 v[4:5], v[156:157], v[6:7]
	s_waitcnt vmcnt(0)
	v_mov_b64_e32 v[90:91], v[94:95]
	v_pk_fma_f32 v[2:3], v[160:161], v[2:3], v[4:5]
	v_mov_b64_e32 v[92:93], v[96:97]
	v_pk_add_f32 v[114:115], v[48:49], v[2:3]
	s_cbranch_scc1 .LBB0_498

.LBB0_509:
	v_mfma_f32_32x32x16_bf16 v[50:65], v[138:141], v[78:81], 0
	v_mul_f32_e64 v172, v156, v164
	v_mul_f32_e64 v173, v157, v165
	v_mul_f32_e64 v164, v160, v164
	v_mul_f32_e64 v165, v161, v165
	v_fma_f32 v172, v160, v162, -v172
	v_fma_f32 v173, v161, v163, -v173
	v_pk_fma_f32 v[162:163], v[156:157], v[162:163], v[164:165]
	s_add_i32 s76, s76, 1
	v_lshl_add_u64 v[158:159], v[158:159], 0, s[70:71]
	s_cmp_eq_u32 s76, 16
	v_mfma_f32_32x32x16_bf16 v[2:17], v[138:141], v[66:69], 0
	s_nop 0
	v_mov_b32_e32 v170, v50
	v_mfma_f32_32x32x16_bf16 v[18:33], v[138:141], v[70:73], 0
	s_nop 8
	v_mov_b32_e32 v171, v2
	v_add_f32_e64 v172, v172, v170
	v_add_f32_e64 v173, v173, v171
	v_mov_b32_e32 v2, v51
	v_mfma_f32_32x32x16_bf16 v[34:49], v[138:141], v[74:77], 0
	v_mov_b32_e32 v188, v18
	s_nop 10
	v_mov_b32_e32 v189, v34
	v_pk_add_f32 v[170:171], v[162:163], v[188:189]
	v_mov_b32_e32 v34, v19
	v_pk_mul_f32 v[18:19], v[156:157], v[170:171]
	s_nop 0
	v_pk_fma_f32 v[18:19], v[160:161], v[172:173], v[18:19] neg_lo:[0,0,1] neg_hi:[0,0,1]
	s_nop 0
	v_pk_add_f32 v[50:51], v[2:3], v[18:19]
	v_pk_mul_f32 v[2:3], v[160:161], v[170:171]
	v_mov_b32_e32 v18, v52
	v_pk_fma_f32 v[2:3], v[156:157], v[172:173], v[2:3]
	v_mov_b32_e32 v19, v4
	v_pk_add_f32 v[2:3], v[34:35], v[2:3]
	v_mov_b32_e32 v34, v20
	v_pk_mul_f32 v[162:163], v[156:157], v[2:3]
	v_mov_b32_e32 v35, v36
	v_pk_fma_f32 v[162:163], v[160:161], v[50:51], v[162:163] neg_lo:[0,0,1] neg_hi:[0,0,1]
	v_mov_b32_e32 v36, v21
	v_pk_add_f32 v[188:189], v[18:19], v[162:163]
	v_pk_mul_f32 v[18:19], v[156:157], v[50:51]
	v_mov_b32_e32 v4, v53
	v_pk_fma_f32 v[18:19], v[160:161], v[2:3], v[18:19]
	s_nop 0
	v_pk_add_f32 v[18:19], v[34:35], v[18:19]
	v_mov_b32_e32 v34, v54
	v_pk_mul_f32 v[20:21], v[156:157], v[18:19]
	v_mov_b32_e32 v35, v6
	v_pk_fma_f32 v[20:21], v[160:161], v[188:189], v[20:21] neg_lo:[0,0,1] neg_hi:[0,0,1]
	v_mov_b32_e32 v6, v55
	v_pk_add_f32 v[20:21], v[4:5], v[20:21]
	v_pk_mul_f32 v[4:5], v[156:157], v[188:189]
	s_nop 0
	v_pk_fma_f32 v[4:5], v[160:161], v[18:19], v[4:5]
	s_nop 0
	v_pk_add_f32 v[4:5], v[36:37], v[4:5]
	v_mov_b32_e32 v36, v22
	v_pk_mul_f32 v[52:53], v[156:157], v[4:5]
	v_mov_b32_e32 v37, v38
	v_pk_fma_f32 v[52:53], v[160:161], v[20:21], v[52:53] neg_lo:[0,0,1] neg_hi:[0,0,1]
	v_mov_b32_e32 v38, v23
	v_pk_add_f32 v[34:35], v[34:35], v[52:53]
	v_pk_mul_f32 v[52:53], v[156:157], v[20:21]
	s_nop 0
	v_pk_fma_f32 v[52:53], v[160:161], v[4:5], v[52:53]
	s_nop 0
	v_pk_add_f32 v[36:37], v[36:37], v[52:53]
	v_mov_b32_e32 v52, v24
	v_pk_mul_f32 v[22:23], v[156:157], v[36:37]
	v_mov_b32_e32 v53, v40
	v_pk_fma_f32 v[22:23], v[160:161], v[34:35], v[22:23] neg_lo:[0,0,1] neg_hi:[0,0,1]
	v_mov_b32_e32 v40, v25
	v_pk_add_f32 v[6:7], v[6:7], v[22:23]
	v_pk_mul_f32 v[22:23], v[156:157], v[34:35]
	s_nop 0
	v_pk_fma_f32 v[22:23], v[160:161], v[36:37], v[22:23]
	s_nop 0
	v_pk_add_f32 v[22:23], v[38:39], v[22:23]
	v_mov_b32_e32 v38, v56
	v_pk_mul_f32 v[54:55], v[156:157], v[22:23]
	v_mov_b32_e32 v39, v8
	v_pk_fma_f32 v[54:55], v[160:161], v[6:7], v[54:55] neg_lo:[0,0,1] neg_hi:[0,0,1]
	v_mov_b32_e32 v8, v57
	v_pk_add_f32 v[38:39], v[38:39], v[54:55]
	v_pk_mul_f32 v[54:55], v[156:157], v[6:7]
	s_nop 0
	v_pk_fma_f32 v[54:55], v[160:161], v[22:23], v[54:55]
	s_nop 0
	v_pk_add_f32 v[52:53], v[52:53], v[54:55]
	v_mov_b32_e32 v54, v26
	v_pk_mul_f32 v[24:25], v[156:157], v[52:53]
	v_mov_b32_e32 v55, v42
	v_pk_fma_f32 v[24:25], v[160:161], v[38:39], v[24:25] neg_lo:[0,0,1] neg_hi:[0,0,1]
	v_mov_b32_e32 v42, v27
	v_pk_add_f32 v[8:9], v[8:9], v[24:25]
	v_pk_mul_f32 v[24:25], v[156:157], v[38:39]
	s_nop 0
	v_pk_fma_f32 v[24:25], v[160:161], v[52:53], v[24:25]
	s_nop 0
	v_pk_add_f32 v[24:25], v[40:41], v[24:25]
	v_mov_b32_e32 v40, v58
	v_pk_mul_f32 v[56:57], v[156:157], v[24:25]
	v_mov_b32_e32 v41, v10
	v_pk_fma_f32 v[56:57], v[160:161], v[8:9], v[56:57] neg_lo:[0,0,1] neg_hi:[0,0,1]
	v_mov_b32_e32 v10, v59
	v_pk_add_f32 v[40:41], v[40:41], v[56:57]
	v_pk_mul_f32 v[56:57], v[156:157], v[8:9]
	s_nop 0
	v_pk_fma_f32 v[56:57], v[160:161], v[24:25], v[56:57]
	s_nop 0
	v_pk_add_f32 v[54:55], v[54:55], v[56:57]
	v_mov_b32_e32 v56, v28
	v_pk_mul_f32 v[26:27], v[156:157], v[54:55]
	v_mov_b32_e32 v57, v44
	v_pk_fma_f32 v[26:27], v[160:161], v[40:41], v[26:27] neg_lo:[0,0,1] neg_hi:[0,0,1]
	v_mov_b32_e32 v44, v29
	v_pk_add_f32 v[10:11], v[10:11], v[26:27]
	v_pk_mul_f32 v[26:27], v[156:157], v[40:41]
	s_nop 0
	v_pk_fma_f32 v[26:27], v[160:161], v[54:55], v[26:27]
	s_nop 0
	v_pk_add_f32 v[26:27], v[42:43], v[26:27]
	v_mov_b32_e32 v42, v60
	v_pk_mul_f32 v[58:59], v[156:157], v[26:27]
	v_mov_b32_e32 v43, v12
	v_pk_fma_f32 v[58:59], v[160:161], v[10:11], v[58:59] neg_lo:[0,0,1] neg_hi:[0,0,1]
	v_mov_b32_e32 v12, v61
	v_pk_add_f32 v[42:43], v[42:43], v[58:59]
	v_pk_mul_f32 v[58:59], v[156:157], v[10:11]
	s_nop 0
	v_pk_fma_f32 v[58:59], v[160:161], v[26:27], v[58:59]
	s_nop 0
	v_pk_add_f32 v[56:57], v[56:57], v[58:59]
	v_mov_b32_e32 v58, v30
	v_pk_mul_f32 v[28:29], v[156:157], v[56:57]
	v_mov_b32_e32 v59, v46
	v_pk_fma_f32 v[28:29], v[160:161], v[42:43], v[28:29] neg_lo:[0,0,1] neg_hi:[0,0,1]
	v_mov_b32_e32 v46, v31
	v_pk_add_f32 v[12:13], v[12:13], v[28:29]
	v_pk_mul_f32 v[28:29], v[156:157], v[42:43]
	s_nop 0
	v_pk_fma_f32 v[28:29], v[160:161], v[56:57], v[28:29]
	s_nop 0
	v_pk_add_f32 v[28:29], v[44:45], v[28:29]
	v_mov_b32_e32 v44, v62
	v_pk_mul_f32 v[60:61], v[156:157], v[28:29]
	v_mov_b32_e32 v45, v14
	v_pk_fma_f32 v[60:61], v[160:161], v[12:13], v[60:61] neg_lo:[0,0,1] neg_hi:[0,0,1]
	v_mov_b32_e32 v14, v63
	v_pk_add_f32 v[44:45], v[44:45], v[60:61]
	v_pk_mul_f32 v[60:61], v[156:157], v[12:13]
	s_nop 0
	v_pk_fma_f32 v[60:61], v[160:161], v[28:29], v[60:61]
	s_nop 0
	v_pk_add_f32 v[58:59], v[58:59], v[60:61]
	v_mov_b32_e32 v60, v32
	v_pk_mul_f32 v[30:31], v[156:157], v[58:59]
	v_mov_b32_e32 v61, v48
	v_pk_fma_f32 v[30:31], v[160:161], v[44:45], v[30:31] neg_lo:[0,0,1] neg_hi:[0,0,1]
	v_mov_b32_e32 v48, v33
	v_pk_add_f32 v[14:15], v[14:15], v[30:31]
	v_pk_mul_f32 v[30:31], v[156:157], v[44:45]
	s_nop 0
	v_pk_fma_f32 v[30:31], v[160:161], v[58:59], v[30:31]
	s_nop 0
	v_pk_add_f32 v[30:31], v[46:47], v[30:31]
	v_mov_b32_e32 v46, v64
	v_pk_mul_f32 v[62:63], v[156:157], v[30:31]
	v_mov_b32_e32 v47, v16
	v_pk_fma_f32 v[62:63], v[160:161], v[14:15], v[62:63] neg_lo:[0,0,1] neg_hi:[0,0,1]
	v_mov_b32_e32 v16, v65
	v_pk_add_f32 v[46:47], v[46:47], v[62:63]
	v_pk_mul_f32 v[62:63], v[156:157], v[14:15]
	s_nop 0
	v_pk_fma_f32 v[62:63], v[160:161], v[30:31], v[62:63]
	s_nop 0
	v_pk_add_f32 v[60:61], v[60:61], v[62:63]
	s_nop 0
	v_pk_mul_f32 v[32:33], v[156:157], v[60:61]
	s_nop 0
	v_pk_fma_f32 v[32:33], v[160:161], v[46:47], v[32:33] neg_lo:[0,0,1] neg_hi:[0,0,1]
	s_nop 0
	v_pk_add_f32 v[162:163], v[16:17], v[32:33]
	v_pk_mul_f32 v[16:17], v[156:157], v[46:47]
	s_nop 0
	v_pk_fma_f32 v[16:17], v[160:161], v[60:61], v[16:17]
	s_nop 0
	v_pk_add_f32 v[164:165], v[48:49], v[16:17]
	v_cvt_pk_bf16_f32 v16, v172, v50
	v_cvt_pk_bf16_f32 v17, v188, v20
	ds_write_b64 v185, v[16:17]
	v_cvt_pk_bf16_f32 v16, v34, v6
	v_cvt_pk_bf16_f32 v17, v38, v8
	ds_write_b64 v185, v[16:17] offset:16
	v_cvt_pk_bf16_f32 v16, v40, v10
	v_cvt_pk_bf16_f32 v17, v42, v12
	ds_write_b64 v185, v[16:17] offset:32
	v_cvt_pk_bf16_f32 v16, v44, v14
	v_cvt_pk_bf16_f32 v17, v46, v162
	ds_write_b64 v185, v[16:17] offset:48
	v_cvt_pk_bf16_f32 v16, v173, v51
	v_cvt_pk_bf16_f32 v17, v189, v21
	ds_write_b64 v185, v[16:17] offset:2304
	v_cvt_pk_bf16_f32 v6, v35, v7
	v_cvt_pk_bf16_f32 v7, v39, v9
	ds_write_b64 v185, v[6:7] offset:2320
	v_cvt_pk_bf16_f32 v6, v41, v11
	v_cvt_pk_bf16_f32 v7, v43, v13
	ds_write_b64 v185, v[6:7] offset:2336
	v_cvt_pk_bf16_f32 v6, v45, v15
	v_cvt_pk_bf16_f32 v7, v47, v163
	ds_write_b64 v185, v[6:7] offset:2352
	v_cvt_pk_bf16_f32 v6, v170, v2
	v_cvt_pk_bf16_f32 v7, v18, v4
	ds_write_b64 v185, v[6:7] offset:4608
	v_cvt_pk_bf16_f32 v6, v36, v22
	v_cvt_pk_bf16_f32 v7, v52, v24
	ds_write_b64 v185, v[6:7] offset:4624
	v_cvt_pk_bf16_f32 v6, v54, v26
	v_cvt_pk_bf16_f32 v7, v56, v28
	ds_write_b64 v185, v[6:7] offset:4640
	v_cvt_pk_bf16_f32 v6, v58, v30
	v_cvt_pk_bf16_f32 v7, v60, v164
	ds_write_b64 v185, v[6:7] offset:4656
	v_cvt_pk_bf16_f32 v2, v171, v3
	v_cvt_pk_bf16_f32 v3, v19, v5
	ds_write_b64 v185, v[2:3] offset:6912
	v_mfma_f32_32x32x16_bf16 v[2:17], v[94:97], v[138:141], 0
	v_cvt_pk_bf16_f32 v18, v37, v23
	v_cvt_pk_bf16_f32 v19, v53, v25
	ds_write_b64 v185, v[18:19] offset:6928
	v_cvt_pk_bf16_f32 v18, v55, v27
	v_cvt_pk_bf16_f32 v19, v57, v29
	ds_write_b64 v185, v[18:19] offset:6944
	v_cvt_pk_bf16_f32 v18, v59, v31
	v_mfma_f32_32x32x16_bf16 v[2:17], v[98:101], v[138:141], v[2:17]
	v_cvt_pk_bf16_f32 v19, v61, v165
	ds_write_b64 v185, v[18:19] offset:6960
	s_waitcnt lgkmcnt(0)
	ds_read_b64_tr_b16 v[18:19], v186
	ds_read_b64_tr_b16 v[20:21], v186 offset:288
	ds_read_b64_tr_b16 v[22:23], v186 offset:1152
	ds_read_b64_tr_b16 v[24:25], v186 offset:1440
	v_mov_b64_e32 v[140:141], v[136:137]
	v_mov_b64_e32 v[138:139], v[134:135]
	s_waitcnt lgkmcnt(2)
	v_mfma_f32_32x32x16_bf16 v[2:17], v[102:105], v[18:21], v[2:17]
	s_waitcnt lgkmcnt(0)
	v_mfma_f32_32x32x16_bf16 v[2:17], v[106:109], v[22:25], v[2:17]
	ds_read_b64_tr_b16 v[18:19], v186 offset:2304
	ds_read_b64_tr_b16 v[20:21], v186 offset:2592
	ds_read_b64_tr_b16 v[22:23], v186 offset:3456
	ds_read_b64_tr_b16 v[24:25], v186 offset:3744
	s_waitcnt lgkmcnt(2)
	v_mfma_f32_32x32x16_bf16 v[2:17], v[110:113], v[18:21], v[2:17]
	s_waitcnt lgkmcnt(0)
	v_mfma_f32_32x32x16_bf16 v[2:17], v[114:117], v[22:25], v[2:17]
	ds_read_b64_tr_b16 v[18:19], v186 offset:4608
	ds_read_b64_tr_b16 v[20:21], v186 offset:4896
	ds_read_b64_tr_b16 v[22:23], v186 offset:5760
	ds_read_b64_tr_b16 v[24:25], v186 offset:6048
	s_waitcnt lgkmcnt(2)
	v_mfma_f32_32x32x16_bf16 v[2:17], v[118:121], v[18:21], v[2:17]
	s_waitcnt lgkmcnt(0)
	v_mfma_f32_32x32x16_bf16 v[2:17], v[122:125], v[22:25], v[2:17]
	ds_read_b64_tr_b16 v[18:19], v186 offset:6912
	ds_read_b64_tr_b16 v[20:21], v186 offset:7200
	ds_read_b64_tr_b16 v[22:23], v186 offset:8064
	ds_read_b64_tr_b16 v[24:25], v186 offset:8352
	s_waitcnt lgkmcnt(0)
	s_waitcnt lgkmcnt(2)
	v_mfma_f32_32x32x16_bf16 v[2:17], v[126:129], v[18:21], v[2:17]
	s_waitcnt lgkmcnt(0)
	v_mfma_f32_32x32x16_bf16 v[2:17], v[130:133], v[22:25], v[2:17]
	s_nop 11
	v_mul_f32_e32 v11, 0x3d372713, v3
	v_mul_f32_e32 v12, 0x3d372713, v4
	v_mul_f32_e32 v11, v3, v11
	v_mul_f32_e32 v12, v4, v12
	v_fma_f32 v11, v3, v11, v3
	v_fma_f32 v12, v4, v12, v4
	v_mul_f32_e32 v11, 0x3fcc422a, v11
	v_mul_f32_e32 v12, 0x3fcc422a, v12
	v_mul_f32_e32 v10, 0x3d372713, v2
	v_mul_f32_e32 v11, 0xbfb8aa3b, v11
	v_mul_f32_e32 v12, 0xbfb8aa3b, v12
	v_mul_f32_e32 v10, v2, v10
	v_exp_f32_e32 v11, v11
	v_exp_f32_e32 v12, v12
	v_fma_f32 v10, v2, v10, v2
	v_mul_f32_e32 v10, 0x3fcc422a, v10
	v_mul_f32_e32 v10, 0xbfb8aa3b, v10
	v_exp_f32_e32 v10, v10
	v_add_f32_e32 v11, 1.0, v11
	v_add_f32_e32 v12, 1.0, v12
	v_mul_f32_e32 v13, 0x3d372713, v5
	v_rcp_f32_e32 v11, v11
	v_rcp_f32_e32 v12, v12
	v_mul_f32_e32 v13, v5, v13
	v_fma_f32 v13, v5, v13, v5
	v_mul_f32_e32 v13, 0x3fcc422a, v13
	v_add_f32_e32 v10, 1.0, v10
	v_mul_f32_e32 v13, 0xbfb8aa3b, v13
	v_rcp_f32_e32 v10, v10
	v_exp_f32_e32 v13, v13
	v_mul_f32_e32 v3, v3, v11
	v_mul_f32_e32 v4, v4, v12
	v_mul_f32_e32 v11, 0x3d372713, v6
	v_mul_f32_e32 v12, 0x3d372713, v7
	v_mul_f32_e32 v11, v6, v11
	v_mul_f32_e32 v12, v7, v12
	v_fma_f32 v11, v6, v11, v6
	v_fma_f32 v12, v7, v12, v7
	v_mul_f32_e32 v11, 0x3fcc422a, v11
	v_mul_f32_e32 v12, 0x3fcc422a, v12
	v_mul_f32_e32 v2, v2, v10
	v_add_f32_e32 v10, 1.0, v13
	v_mul_f32_e32 v11, 0xbfb8aa3b, v11
	v_mul_f32_e32 v12, 0xbfb8aa3b, v12
	v_rcp_f32_e32 v10, v10
	v_exp_f32_e32 v11, v11
	v_exp_f32_e32 v12, v12
	v_mul_f32_e32 v13, 0x3d372713, v9
	v_mul_f32_e32 v5, v5, v10
	v_add_f32_e32 v10, 1.0, v11
	v_add_f32_e32 v11, 1.0, v12
	v_mul_f32_e32 v12, 0x3d372713, v8
	v_mul_f32_e32 v12, v8, v12
	v_mul_f32_e32 v13, v9, v13
	v_fma_f32 v12, v8, v12, v8
	v_fma_f32 v13, v9, v13, v9
	v_mul_f32_e32 v12, 0x3fcc422a, v12
	v_mul_f32_e32 v13, 0x3fcc422a, v13
	v_mul_f32_e32 v12, 0xbfb8aa3b, v12
	v_mul_f32_e32 v13, 0xbfb8aa3b, v13
	v_exp_f32_e32 v12, v12
	v_exp_f32_e32 v13, v13
	v_rcp_f32_e32 v10, v10
	v_rcp_f32_e32 v11, v11
	v_add_f32_e32 v12, 1.0, v12
	v_add_f32_e32 v13, 1.0, v13
	v_rcp_f32_e32 v12, v12
	v_rcp_f32_e32 v13, v13
	v_cvt_pk_bf16_f32 v2, v2, v3
	v_cvt_pk_bf16_f32 v3, v4, v5
	v_mul_f32_e32 v6, v6, v10
	v_mul_f32_e32 v7, v7, v11
	v_mul_f32_e32 v8, v8, v12
	v_mul_f32_e32 v9, v9, v13
	v_cvt_pk_bf16_f32 v4, v6, v7
	v_cvt_pk_bf16_f32 v5, v8, v9
	global_store_dwordx2 v[168:169], v[2:3], off
	global_store_dwordx2 v[168:169], v[4:5], off offset:16
	v_lshl_add_u64 v[168:169], v[168:169], 0, s[70:71]
	s_cbranch_scc1 .LBB0_493
	s_waitcnt vmcnt(2)
	v_mov_b64_e32 v[136:137], v[84:85]
	v_mov_b64_e32 v[134:135], v[82:83]
	v_mov_b64_e32 v[82:83], v[90:91]
	v_mov_b64_e32 v[84:85], v[92:93]
	v_mov_b64_e32 v[92:93], v[88:89]
	s_cmp_gt_u32 s76, 11
	v_mov_b64_e32 v[90:91], v[86:87]
	s_cbranch_scc1 .LBB0_509
	s_branch .Lssm2_load

.Lssm2_load:
	global_load_dwordx4 v[86:89], v[158:159], off
	s_branch .LBB0_509

.LBB0_520:
	v_mov_b32_e32 v218, v3
	s_and_b32 s56, s60, 0xffffff80
	s_sub_i32 s79, s66, s56
	s_lshl_b32 s4, s60, 8
	v_add_u32_e32 v184, s79, v198
	s_and_b32 s8, s4, 0x7800
	v_ashrrev_i32_e32 v185, 31, v184
	v_lshl_add_u64 v[182:183], v[184:185], 0, s[8:9]
	s_and_b32 s78, s60, 7
	v_lshlrev_b64 v[4:5], 11, v[182:183]
	v_lshl_add_u64 v[4:5], s[38:39], 0, v[4:5]
	s_lshl_b32 s4, s78, 8
	s_mov_b32 s5, s9
	v_lshl_add_u64 v[4:5], v[4:5], 0, s[4:5]
	v_lshl_add_u64 v[4:5], v[4:5], 0, s[14:15]
	v_mov_b32_e32 v179, v3
	v_lshl_add_u64 v[4:5], v[4:5], 0, v[178:179]
	global_load_dwordx4 v[114:117], v[4:5], off
	global_load_dwordx4 v[118:121], v[4:5], off offset:32
	global_load_dwordx4 v[122:125], v[4:5], off offset:64
	global_load_dwordx4 v[126:129], v[4:5], off offset:96
	s_add_i32 s5, s78, 1
	s_ashr_i32 s57, s60, 6
	v_cvt_f32_ubyte0_e32 v18, s5
	s_and_b32 s58, s57, -2
	v_cmp_lt_f32_e32 vcc, s72, v18
	s_and_b64 s[60:61], vcc, exec
	s_cselect_b32 s59, 0xffffffc0, 0
	s_lshl_b32 s5, s8, 11
	s_add_u32 s8, s63, s5
	s_addc_u32 s61, s64, 0
	s_add_u32 s60, s8, s4
	s_addc_u32 s61, s61, 0
	s_add_u32 s5, s65, s5
	s_addc_u32 s8, s70, 0
	s_add_u32 s4, s5, s4
	s_addc_u32 s5, s8, 0
	s_sub_i32 s8, 31, s58
	v_mov_b32_e32 v181, v3
	v_lshl_or_b32 v2, s8, 6, v199
	v_lshl_add_u64 v[186:187], s[60:61], 0, v[180:181]
	v_lshlrev_b64 v[6:7], 11, v[2:3]
	s_lshl_b32 s60, s58, 6
	v_lshl_add_u64 v[8:9], v[186:187], 0, v[6:7]
	v_cndmask_b32_e32 v19, 0, v215, vcc
	v_lshl_add_u64 v[188:189], s[4:5], 0, v[180:181]
	v_subrev_u32_e32 v4, s60, v199
	v_add_co_u32_e32 v12, vcc, s73, v8
	v_add_u32_e32 v2, 0x780, v4
	v_lshl_add_u64 v[6:7], v[188:189], 0, v[6:7]
	v_addc_co_u32_e32 v13, vcc, 0, v9, vcc
	v_lshlrev_b64 v[10:11], 11, v[2:3]
	v_add_co_u32_e32 v14, vcc, s73, v6
	v_lshl_add_u64 v[16:17], v[186:187], 0, v[10:11]
	s_nop 0
	v_addc_co_u32_e32 v15, vcc, 0, v7, vcc
	global_load_dwordx4 v[134:137], v[8:9], off
	global_load_dwordx4 v[154:157], v[12:13], off
	global_load_dwordx4 v[146:149], v[6:7], off
	global_load_dwordx4 v[158:161], v[14:15], off
	v_add_co_u32_e32 v6, vcc, s73, v16
	v_lshl_add_u64 v[10:11], v[188:189], 0, v[10:11]
	s_nop 0
	v_addc_co_u32_e32 v7, vcc, 0, v17, vcc
	v_add_co_u32_e32 v8, vcc, s73, v10
	s_waitcnt vmcnt(7)
	v_and_b32_e32 v5, 0xffff0000, v114
	v_lshlrev_b32_e32 v2, 16, v114
	v_mul_f32_e32 v5, v5, v5
	v_addc_co_u32_e32 v9, vcc, 0, v11, vcc
	global_load_dwordx4 v[130:133], v[16:17], off
	global_load_dwordx4 v[142:145], v[6:7], off
	global_load_dwordx4 v[138:141], v[10:11], off
	global_load_dwordx4 v[150:153], v[8:9], off
	v_lshlrev_b32_e32 v6, 16, v115
	v_fmac_f32_e32 v5, v2, v2
	v_and_b32_e32 v7, 0xffff0000, v115
	v_fmac_f32_e32 v5, v6, v6
	v_lshlrev_b32_e32 v8, 16, v116
	v_fmac_f32_e32 v5, v7, v7
	v_and_b32_e32 v9, 0xffff0000, v116
	v_fmac_f32_e32 v5, v8, v8
	v_lshlrev_b32_e32 v10, 16, v117
	v_fmac_f32_e32 v5, v9, v9
	v_and_b32_e32 v11, 0xffff0000, v117
	v_fmac_f32_e32 v5, v10, v10
	s_waitcnt vmcnt(10)
	v_lshlrev_b32_e32 v12, 16, v118
	v_fmac_f32_e32 v5, v11, v11
	v_and_b32_e32 v13, 0xffff0000, v118
	v_fmac_f32_e32 v5, v12, v12
	v_lshlrev_b32_e32 v14, 16, v119
	v_fmac_f32_e32 v5, v13, v13
	v_and_b32_e32 v15, 0xffff0000, v119
	v_fmac_f32_e32 v5, v14, v14
	v_lshlrev_b32_e32 v16, 16, v120
	v_fmac_f32_e32 v5, v15, v15
	v_and_b32_e32 v17, 0xffff0000, v120
	v_fmac_f32_e32 v5, v16, v16
	v_lshlrev_b32_e32 v20, 16, v121
	v_fmac_f32_e32 v5, v17, v17
	v_and_b32_e32 v21, 0xffff0000, v121
	v_fmac_f32_e32 v5, v20, v20
	v_fmac_f32_e32 v5, v21, v21
	s_waitcnt vmcnt(9)
	v_lshlrev_b32_e32 v2, 16, v122
	v_fmac_f32_e32 v5, v2, v2
	v_and_b32_e32 v2, 0xffff0000, v122
	v_fmac_f32_e32 v5, v2, v2
	v_lshlrev_b32_e32 v2, 16, v123
	v_fmac_f32_e32 v5, v2, v2
	v_and_b32_e32 v2, 0xffff0000, v123
	v_fmac_f32_e32 v5, v2, v2
	v_lshlrev_b32_e32 v2, 16, v124
	v_fmac_f32_e32 v5, v2, v2
	v_and_b32_e32 v2, 0xffff0000, v124
	v_fmac_f32_e32 v5, v2, v2
	v_lshlrev_b32_e32 v2, 16, v125
	v_fmac_f32_e32 v5, v2, v2
	v_and_b32_e32 v2, 0xffff0000, v125
	v_fmac_f32_e32 v5, v2, v2
	s_waitcnt vmcnt(8)
	v_lshlrev_b32_e32 v2, 16, v126
	v_fmac_f32_e32 v5, v2, v2
	v_and_b32_e32 v2, 0xffff0000, v126
	v_fmac_f32_e32 v5, v2, v2
	v_lshlrev_b32_e32 v2, 16, v127
	v_fmac_f32_e32 v5, v2, v2
	v_and_b32_e32 v2, 0xffff0000, v127
	v_fmac_f32_e32 v5, v2, v2
	v_lshlrev_b32_e32 v2, 16, v128
	v_fmac_f32_e32 v5, v2, v2
	v_and_b32_e32 v2, 0xffff0000, v128
	v_fmac_f32_e32 v5, v2, v2
	v_lshlrev_b32_e32 v2, 16, v129
	v_fmac_f32_e32 v5, v2, v2
	v_and_b32_e32 v2, 0xffff0000, v129
	v_fmac_f32_e32 v5, v2, v2
	ds_bpermute_b32 v2, v197, v5
	v_sub_f32_e32 v6, v19, v18
	v_exp_f32_e32 v6, v6
	s_waitcnt lgkmcnt(0)
	v_add_f32_e32 v2, v5, v2
	v_mul_f32_e32 v5, 0x4f800000, v2
	v_cmp_gt_f32_e32 vcc, s71, v2
	v_ldexp_f32 v6, v6, s59
	v_mul_f32_e32 v190, 0x3fb8aa3b, v6
	v_cndmask_b32_e32 v2, v2, v5, vcc
	v_sqrt_f32_e32 v5, v2
	s_nop 0
	v_add_u32_e32 v6, -1, v5
	v_fma_f32 v7, -v6, v5, v2
	v_cmp_ge_f32_e64 s[4:5], 0, v7
	v_add_u32_e32 v7, 1, v5
	s_nop 0
	v_cndmask_b32_e64 v6, v5, v6, s[4:5]
	v_fma_f32 v5, -v7, v5, v2
	v_cmp_lt_f32_e64 s[4:5], 0, v5
	s_nop 1
	v_cndmask_b32_e64 v5, v6, v7, s[4:5]
	v_mul_f32_e32 v6, 0x37800000, v5
	v_cndmask_b32_e32 v5, v5, v6, vcc
	v_cmp_class_f32_e32 vcc, v2, v200
	s_nop 1
	v_cndmask_b32_e32 v2, v5, v2, vcc
	v_mul_f32_e32 v5, v201, v2
	v_fmaak_f32 v2, 2.0, v5, 0x42200000
	v_div_scale_f32 v6, s[4:5], v190, v190, v2
	v_rcp_f32_e32 v7, v6
	s_nop 0
	v_fma_f32 v8, -v6, v7, 1.0
	v_fmac_f32_e32 v7, v8, v7
	v_div_scale_f32 v8, vcc, v2, v190, v2
	v_mul_f32_e32 v9, v8, v7
	v_fma_f32 v10, -v6, v9, v8
	v_fmac_f32_e32 v9, v10, v7
	v_fma_f32 v6, -v6, v9, v8
	v_div_fmas_f32 v6, v6, v7, v9
	v_div_fixup_f32 v2, v6, v190, v2
	ds_bpermute_b32 v6, v192, v2
	s_waitcnt lgkmcnt(0)
	v_max_f32_e32 v6, v6, v6
	v_max_f32_e32 v2, v2, v6
	ds_bpermute_b32 v6, v193, v2
	s_waitcnt lgkmcnt(0)
	v_max_f32_e32 v6, v6, v6
	v_max_f32_e32 v2, v2, v6
	ds_bpermute_b32 v6, v194, v2
	s_waitcnt lgkmcnt(0)
	v_max_f32_e32 v6, v6, v6
	v_max_f32_e32 v2, v2, v6
	ds_bpermute_b32 v6, v195, v2
	s_waitcnt lgkmcnt(0)
	v_max_f32_e32 v6, v6, v6
	v_max_f32_e32 v2, v2, v6
	ds_bpermute_b32 v6, v196, v2
	s_and_saveexec_b64 s[4:5], s[0:1]
	s_cbranch_execz .LBB0_526
	s_waitcnt lgkmcnt(0)
	v_max_f32_e32 v6, v6, v6
	v_max_f32_e32 v2, v2, v2
	v_max_f32_e32 v2, v2, v6
	v_mov_b32_e32 v6, s67
	ds_write_b32 v6, v2

.LBB0_528:
	s_add_i32 s4, 0, 0x22800
	v_mov_b32_e32 v2, s4
	s_waitcnt lgkmcnt(0)
	s_barrier
	s_and_saveexec_b64 s[98:99], s[26:27]
	v_mov_b32_e32 v218, 1
	global_atomic_add v218, v3, v218, s[6:7] sc0
	s_or_b64 exec, exec, s[98:99]
	ds_read_b128 v[6:9], v2
	v_mov_b32_e32 v2, s74
	ds_read_b128 v[10:13], v2
	s_sub_i32 s4, 0x741, s56
	s_sub_i32 s8, 32, s58
	s_waitcnt lgkmcnt(1)
	v_max_f32_e32 v2, v7, v7
	v_max_f32_e32 v4, v6, v6
	v_max_f32_e32 v2, v4, v2
	v_cvt_f32_i32_e32 v4, s4
	v_max3_f32 v2, v2, v8, v9
	s_waitcnt lgkmcnt(0)
	v_max3_f32 v2, v2, v10, v11
	v_max3_f32 v2, v2, v12, v13
	v_sub_f32_e32 v4, v4, v2
	v_mul_f32_e32 v6, 0x3c800000, v4
	v_floor_f32_e32 v6, v6
	v_cvt_i32_f32_e32 v6, v6
	v_cmp_nle_f32_e32 vcc, 0, v4
	v_mov_b32_e32 v81, 0
	v_mov_b32_e32 v80, 0
	v_readfirstlane_b32 s4, v6
	s_not_b32 s4, s4
	s_add_i32 s4, s8, s4
	s_max_i32 s58, s4, 2
	s_and_b64 s[4:5], vcc, exec
	s_cselect_b32 s8, s8, s58
	s_cmp_lt_i32 s8, 1
	v_mov_b32_e32 v79, 0
	v_mov_b32_e32 v78, 0
	v_mov_b32_e32 v77, 0
	v_mov_b32_e32 v76, 0
	v_mov_b32_e32 v75, 0
	v_mov_b32_e32 v74, 0
	v_mov_b32_e32 v73, 0
	v_mov_b32_e32 v72, 0
	v_mov_b32_e32 v71, 0
	v_mov_b32_e32 v70, 0
	v_mov_b32_e32 v69, 0
	v_mov_b32_e32 v68, 0
	v_mov_b32_e32 v67, 0
	v_mov_b32_e32 v66, 0
	v_mov_b32_e32 v65, 0
	v_mov_b32_e32 v64, 0
	v_mov_b32_e32 v63, 0
	v_mov_b32_e32 v62, 0
	v_mov_b32_e32 v61, 0
	v_mov_b32_e32 v60, 0
	v_mov_b32_e32 v59, 0
	v_mov_b32_e32 v58, 0
	v_mov_b32_e32 v57, 0
	v_mov_b32_e32 v56, 0
	v_mov_b32_e32 v55, 0
	v_mov_b32_e32 v54, 0
	v_mov_b32_e32 v53, 0
	v_mov_b32_e32 v52, 0
	v_mov_b32_e32 v51, 0
	v_mov_b32_e32 v50, 0
	v_mov_b32_e32 v49, 0
	v_mov_b32_e32 v48, 0
	v_mov_b32_e32 v47, 0
	v_mov_b32_e32 v46, 0
	v_mov_b32_e32 v45, 0
	v_mov_b32_e32 v44, 0
	v_mov_b32_e32 v43, 0
	v_mov_b32_e32 v42, 0
	v_mov_b32_e32 v41, 0
	v_mov_b32_e32 v40, 0
	v_mov_b32_e32 v39, 0
	v_mov_b32_e32 v38, 0
	v_mov_b32_e32 v37, 0
	v_mov_b32_e32 v36, 0
	v_mov_b32_e32 v35, 0
	v_mov_b32_e32 v34, 0
	v_mov_b32_e32 v33, 0
	v_mov_b32_e32 v32, 0
	v_mov_b32_e32 v31, 0
	v_mov_b32_e32 v30, 0
	v_mov_b32_e32 v29, 0
	v_mov_b32_e32 v28, 0
	v_mov_b32_e32 v27, 0
	v_mov_b32_e32 v26, 0
	v_mov_b32_e32 v25, 0
	v_mov_b32_e32 v24, 0
	v_mov_b32_e32 v23, 0
	v_mov_b32_e32 v22, 0
	v_mov_b32_e32 v21, 0
	v_mov_b32_e32 v20, 0
	v_mov_b32_e32 v19, 0
	v_mov_b32_e32 v18, 0
	v_mov_b32_e32 v168, 0
	s_cbranch_scc1 .LBB0_559
	v_fmaak_f32 v2, v190, v2, 0xc2200000
	v_mul_f32_e32 v2, 0.5, v2
	v_cmp_gt_f32_e32 vcc, s75, v2
	s_lshl_b32 s57, s57, 6
	v_mov_b32_e32 v16, v3
	v_mov_b32_e32 v17, v3
	v_cmp_ngt_f32_e64 s[4:5], s75, v2
	v_cndmask_b32_e32 v185, 0, v5, vcc
	s_and_b32 s57, s57, 0xffffff80
	v_mov_b32_e32 v2, v3
	v_mov_b32_e32 v4, v3
	v_mov_b32_e32 v5, v3
	v_mov_b32_e32 v6, v3
	v_mov_b32_e32 v7, v3
	v_mov_b32_e32 v8, v3
	v_mov_b32_e32 v9, v3
	v_mov_b32_e32 v10, v3
	v_mov_b32_e32 v11, v3
	v_mov_b32_e32 v12, v3
	v_mov_b32_e32 v13, v3
	v_mov_b32_e32 v14, v3
	v_mov_b32_e32 v15, v3
	v_mov_b64_e32 v[32:33], v[16:17]
	v_mov_b64_e32 v[48:49], v[16:17]
	v_mov_b64_e32 v[64:65], v[16:17]
	v_mov_b64_e32 v[80:81], v[16:17]
	s_addk_i32 s79, 0x79f
	s_add_i32 s80, s8, -3
	s_add_i32 s81, s8, -2
	s_add_i32 s82, s8, -4
	s_mov_b32 s83, 0
	v_mul_f32_e32 v219, 0x42000000, v190
	v_mov_b32_e32 v191, v190
	s_sub_i32 s84, 0, s57
	v_add_u32_e32 v220, s56, v167
	v_mov_b32_e32 v168, 0
	s_mov_b64 s[58:59], -1
	v_mov_b32_e32 v221, v199
	v_mov_b32_e32 v222, v166
	v_mov_b64_e32 v[30:31], v[14:15]
	v_mov_b64_e32 v[28:29], v[12:13]
	v_mov_b64_e32 v[26:27], v[10:11]
	v_mov_b64_e32 v[24:25], v[8:9]
	v_mov_b64_e32 v[22:23], v[6:7]
	v_mov_b64_e32 v[20:21], v[4:5]
	v_mov_b64_e32 v[18:19], v[2:3]
	v_mov_b64_e32 v[46:47], v[14:15]
	v_mov_b64_e32 v[44:45], v[12:13]
	v_mov_b64_e32 v[42:43], v[10:11]
	v_mov_b64_e32 v[40:41], v[8:9]
	v_mov_b64_e32 v[38:39], v[6:7]
	v_mov_b64_e32 v[36:37], v[4:5]
	v_mov_b64_e32 v[34:35], v[2:3]
	v_mov_b64_e32 v[62:63], v[14:15]
	v_mov_b64_e32 v[60:61], v[12:13]
	v_mov_b64_e32 v[58:59], v[10:11]
	v_mov_b64_e32 v[56:57], v[8:9]
	v_mov_b64_e32 v[54:55], v[6:7]
	v_mov_b64_e32 v[52:53], v[4:5]
	v_mov_b64_e32 v[50:51], v[2:3]
	v_mov_b64_e32 v[78:79], v[14:15]
	v_mov_b64_e32 v[76:77], v[12:13]
	v_mov_b64_e32 v[74:75], v[10:11]
	v_mov_b64_e32 v[72:73], v[8:9]
	v_mov_b64_e32 v[70:71], v[6:7]
	v_mov_b64_e32 v[68:69], v[4:5]
	v_mov_b64_e32 v[66:67], v[2:3]
	s_mov_b32 s85, 0
	s_branch .LBB0_532

.LBB0_532:
	s_add_i32 s60, s84, s83
	s_add_i32 s56, s60, 0x7c0
	s_cmp_gt_i32 s56, s79
	s_cbranch_scc1 .LBB0_541
	v_add_u32_e32 v16, v206, v205
	ds_read_b128 v[4:7], v16
	ds_read_b128 v[8:11], v16 offset:32
	v_add3_u32 v2, s84, v220, 64
	v_cvt_f32_i32_e32 v2, v2
	s_andn2_b64 vcc, exec, s[58:59]
	v_fma_f32 v2, v190, v2, -v185
	v_fma_f32 v82, 0, v190, v2
	v_add_f32_e32 v83, v190, v2
	v_pk_fma_f32 v[84:85], v[190:191], s[16:17], v[2:3] op_sel_hi:[1,1,0]
	v_pk_fma_f32 v[86:87], v[190:191], s[18:19], v[2:3] op_sel_hi:[1,1,0]
	v_pk_fma_f32 v[88:89], v[190:191], s[20:21], v[2:3] op_sel_hi:[1,1,0]
	v_pk_fma_f32 v[90:91], v[190:191], s[22:23], v[2:3] op_sel_hi:[1,1,0]
	v_pk_fma_f32 v[92:93], v[190:191], s[24:25], v[2:3] op_sel_hi:[1,1,0]
	v_pk_fma_f32 v[94:95], v[190:191], s[36:37], v[2:3] op_sel_hi:[1,1,0]
	v_pk_fma_f32 v[96:97], v[190:191], s[54:55], v[2:3] op_sel_hi:[1,1,0]
	v_add_f32_e32 v2, v219, v2
	v_fma_f32 v98, 0, v190, v2
	s_waitcnt lgkmcnt(1)
	v_mfma_f32_32x32x16_bf16 v[82:97], v[4:7], v[114:117], v[82:97]
	v_add_f32_e32 v99, v190, v2
	v_fma_f32 v100, v190, s16, v2
	v_fma_f32 v101, v191, s17, v2
	v_fma_f32 v102, v190, s18, v2
	v_fma_f32 v103, v191, s19, v2
	v_pk_fma_f32 v[104:105], v[190:191], s[20:21], v[2:3] op_sel_hi:[1,1,0]
	v_pk_fma_f32 v[106:107], v[190:191], s[22:23], v[2:3] op_sel_hi:[1,1,0]
	v_pk_fma_f32 v[108:109], v[190:191], s[24:25], v[2:3] op_sel_hi:[1,1,0]
	v_pk_fma_f32 v[110:111], v[190:191], s[36:37], v[2:3] op_sel_hi:[1,1,0]
	s_waitcnt lgkmcnt(0)
	v_mfma_f32_32x32x16_bf16 v[82:97], v[8:11], v[118:121], v[82:97]
	ds_read_b128 v[4:7], v16 offset:64
	ds_read_b128 v[8:11], v16 offset:96
	v_fma_f32 v112, v190, s54, v2
	v_fma_f32 v113, v191, s55, v2
	s_waitcnt lgkmcnt(1)
	v_mfma_f32_32x32x16_bf16 v[82:97], v[4:7], v[122:125], v[82:97]
	ds_read_b128 v[4:7], v16 offset:8704
	ds_read_b128 v[12:15], v16 offset:8736
	s_waitcnt lgkmcnt(1)
	v_mfma_f32_32x32x16_bf16 v[98:113], v[4:7], v[114:117], v[98:113]
	s_waitcnt lgkmcnt(0)
	v_mfma_f32_32x32x16_bf16 v[98:113], v[12:15], v[118:121], v[98:113]
	v_mfma_f32_32x32x16_bf16 v[82:97], v[8:11], v[126:129], v[82:97]
	ds_read_b128 v[4:7], v16 offset:8768
	ds_read_b128 v[224:227], v16 offset:8800
	ds_read_b64_tr_b16 v[12:13], v207 offset:17408
	ds_read_b64_tr_b16 v[14:15], v207 offset:19968
	ds_read_b64_tr_b16 v[8:9], v207 offset:17472
	ds_read_b64_tr_b16 v[10:11], v207 offset:20032
	s_waitcnt lgkmcnt(5)
	v_mfma_f32_32x32x16_bf16 v[98:113], v[4:7], v[122:125], v[98:113]
	ds_read_b64_tr_b16 v[162:163], v207 offset:17536
	ds_read_b64_tr_b16 v[164:165], v207 offset:20096
	ds_read_b64_tr_b16 v[4:5], v207 offset:17600
	ds_read_b64_tr_b16 v[6:7], v207 offset:20160
	s_waitcnt lgkmcnt(8)
	v_mfma_f32_32x32x16_bf16 v[98:113], v[224:227], v[126:129], v[98:113]
	s_cbranch_vccnz .LBB0_535
	v_add_u32_e32 v2, s84, v222
	v_add_u32_e32 v17, 0x7e0, v2
	v_add_u32_e32 v16, 0x7c0, v2
	v_cmp_le_i32_e32 vcc, v17, v184
	s_nop 6
	v_cndmask_b32_e32 v98, v217, v98, vcc
	v_cmp_lt_i32_e32 vcc, v16, v184
	s_nop 1
	v_cndmask_b32_e32 v83, v217, v83, vcc
	v_cmp_le_i32_e32 vcc, v16, v184
	v_add_u32_e32 v16, 0x7e1, v2
	s_nop 0
	v_cndmask_b32_e32 v82, v217, v82, vcc
	v_cmp_le_i32_e32 vcc, v16, v184
	v_add_u32_e32 v16, 0x7c2, v2
	s_nop 0
	v_cndmask_b32_e32 v99, v217, v99, vcc
	v_cmp_le_i32_e32 vcc, v16, v184
	v_add_u32_e32 v16, 0x7e2, v2
	s_nop 0
	v_cndmask_b32_e32 v84, v217, v84, vcc
	v_cmp_le_i32_e32 vcc, v16, v184
	v_add_u32_e32 v16, 0x7c3, v2
	s_nop 0
	v_cndmask_b32_e32 v100, v217, v100, vcc
	v_cmp_le_i32_e32 vcc, v16, v184
	v_add_u32_e32 v16, 0x7e3, v2
	s_nop 0
	v_cndmask_b32_e32 v85, v217, v85, vcc
	v_cmp_le_i32_e32 vcc, v16, v184
	v_add_u32_e32 v16, 0x7c8, v2
	s_nop 0
	v_cndmask_b32_e32 v101, v217, v101, vcc
	v_cmp_le_i32_e32 vcc, v16, v184
	v_add_u32_e32 v16, 0x7e8, v2
	s_nop 0
	v_cndmask_b32_e32 v86, v217, v86, vcc
	v_cmp_le_i32_e32 vcc, v16, v184
	v_add_u32_e32 v16, 0x7c9, v2
	s_nop 0
	v_cndmask_b32_e32 v102, v217, v102, vcc
	v_cmp_le_i32_e32 vcc, v16, v184
	v_add_u32_e32 v16, 0x7e9, v2
	s_nop 0
	v_cndmask_b32_e32 v87, v217, v87, vcc
	v_cmp_le_i32_e32 vcc, v16, v184
	v_add_u32_e32 v16, 0x7ca, v2
	s_nop 0
	v_cndmask_b32_e32 v103, v217, v103, vcc
	v_cmp_le_i32_e32 vcc, v16, v184
	v_add_u32_e32 v16, 0x7ea, v2
	s_nop 0
	v_cndmask_b32_e32 v88, v217, v88, vcc
	v_cmp_le_i32_e32 vcc, v16, v184
	v_add_u32_e32 v16, 0x7cb, v2
	s_nop 0
	v_cndmask_b32_e32 v104, v217, v104, vcc
	v_cmp_le_i32_e32 vcc, v16, v184
	v_add_u32_e32 v16, 0x7eb, v2
	s_nop 0
	v_cndmask_b32_e32 v89, v217, v89, vcc
	v_cmp_le_i32_e32 vcc, v16, v184
	v_add_u32_e32 v16, 0x7d0, v2
	s_nop 0
	v_cndmask_b32_e32 v105, v217, v105, vcc
	v_cmp_le_i32_e32 vcc, v16, v184
	v_add_u32_e32 v16, 0x7f0, v2
	s_nop 0
	v_cndmask_b32_e32 v90, v217, v90, vcc
	v_cmp_le_i32_e32 vcc, v16, v184
	v_add_u32_e32 v16, 0x7d1, v2
	s_nop 0
	v_cndmask_b32_e32 v106, v217, v106, vcc
	v_cmp_le_i32_e32 vcc, v16, v184
	v_add_u32_e32 v16, 0x7f1, v2
	s_nop 0
	v_cndmask_b32_e32 v91, v217, v91, vcc
	v_cmp_le_i32_e32 vcc, v16, v184
	v_add_u32_e32 v16, 0x7d2, v2
	s_nop 0
	v_cndmask_b32_e32 v107, v217, v107, vcc
	v_cmp_le_i32_e32 vcc, v16, v184
	v_add_u32_e32 v16, 0x7f2, v2
	s_nop 0
	v_cndmask_b32_e32 v92, v217, v92, vcc
	v_cmp_le_i32_e32 vcc, v16, v184
	v_add_u32_e32 v16, 0x7d3, v2
	s_nop 0
	v_cndmask_b32_e32 v108, v217, v108, vcc
	v_cmp_le_i32_e32 vcc, v16, v184
	v_add_u32_e32 v16, 0x7f3, v2
	s_nop 0
	v_cndmask_b32_e32 v93, v217, v93, vcc
	v_cmp_le_i32_e32 vcc, v16, v184
	v_add_u32_e32 v16, 0x7d8, v2
	s_nop 0
	v_cndmask_b32_e32 v109, v217, v109, vcc
	v_cmp_le_i32_e32 vcc, v16, v184
	v_add_u32_e32 v16, 0x7f8, v2
	s_nop 0
	v_cndmask_b32_e32 v94, v217, v94, vcc
	v_cmp_le_i32_e32 vcc, v16, v184
	v_add_u32_e32 v16, 0x7d9, v2
	s_nop 0
	v_cndmask_b32_e32 v110, v217, v110, vcc
	v_cmp_le_i32_e32 vcc, v16, v184
	v_add_u32_e32 v16, 0x7f9, v2
	s_nop 0
	v_cndmask_b32_e32 v95, v217, v95, vcc
	v_cmp_le_i32_e32 vcc, v16, v184
	v_add_u32_e32 v16, 0x7da, v2
	s_nop 0
	v_cndmask_b32_e32 v111, v217, v111, vcc
	v_cmp_le_i32_e32 vcc, v16, v184
	v_add_u32_e32 v16, 0x7fa, v2
	s_nop 0
	v_cndmask_b32_e32 v96, v217, v96, vcc
	v_cmp_le_i32_e32 vcc, v16, v184
	v_add_u32_e32 v16, 0x7db, v2
	v_add_u32_e32 v2, 0x7fb, v2
	v_cndmask_b32_e32 v112, v217, v112, vcc
	v_cmp_le_i32_e32 vcc, v16, v184
	s_nop 1
	v_cndmask_b32_e32 v97, v217, v97, vcc
	v_cmp_le_i32_e32 vcc, v2, v184
	s_nop 1
	v_cndmask_b32_e32 v113, v217, v113, vcc

.LBB0_540:
	v_exp_f32_e32 v82, v82
	v_exp_f32_e32 v83, v83
	v_exp_f32_e32 v84, v84
	v_exp_f32_e32 v85, v85
	ds_read_b64_tr_b16 v[240:241], v207 offset:22528
	ds_read_b64_tr_b16 v[242:243], v207 offset:25088
	ds_read_b64_tr_b16 v[244:245], v207 offset:22592
	ds_read_b64_tr_b16 v[246:247], v207 offset:25152
	ds_read_b64_tr_b16 v[248:249], v207 offset:22656
	ds_read_b64_tr_b16 v[250:251], v207 offset:25216
	ds_read_b64_tr_b16 v[252:253], v207 offset:22720
	ds_read_b64_tr_b16 v[254:255], v207 offset:25280
	v_exp_f32_e32 v86, v86
	v_exp_f32_e32 v87, v87
	v_exp_f32_e32 v88, v88
	v_exp_f32_e32 v89, v89
	v_cvt_pk_bf16_f32 v224, v82, v83
	v_cvt_pk_bf16_f32 v225, v84, v85
	v_cvt_pk_bf16_f32 v226, v86, v87
	v_cvt_pk_bf16_f32 v227, v88, v89
	s_waitcnt lgkmcnt(14)
	v_mfma_f32_32x32x16_bf16 v[66:81], v[12:15], v[224:227], v[66:81]
	v_exp_f32_e32 v90, v90
	v_exp_f32_e32 v91, v91
	v_add_f32_e32 v2, v82, v83
	v_add_f32_e32 v17, v84, v85
	ds_read_b64_tr_b16 v[12:13], v207 offset:27648
	ds_read_b64_tr_b16 v[14:15], v207 offset:30208
	s_waitcnt lgkmcnt(14)
	v_mfma_f32_32x32x16_bf16 v[50:65], v[8:11], v[224:227], v[50:65]
	v_exp_f32_e32 v92, v92
	v_exp_f32_e32 v93, v93
	v_cvt_pk_bf16_f32 v228, v90, v91
	v_add_f32_e32 v2, v2, v86
	v_add_f32_e32 v17, v17, v87
	ds_read_b64_tr_b16 v[8:9], v207 offset:27712
	ds_read_b64_tr_b16 v[10:11], v207 offset:30272
	s_waitcnt lgkmcnt(14)
	v_mfma_f32_32x32x16_bf16 v[34:49], v[162:165], v[224:227], v[34:49]
	v_exp_f32_e32 v94, v94
	v_exp_f32_e32 v95, v95
	v_cvt_pk_bf16_f32 v229, v92, v93
	v_add_f32_e32 v2, v2, v88
	v_add_f32_e32 v17, v17, v89
	ds_read_b64_tr_b16 v[162:163], v207 offset:27776
	ds_read_b64_tr_b16 v[164:165], v207 offset:30336
	s_waitcnt lgkmcnt(14)
	v_mfma_f32_32x32x16_bf16 v[18:33], v[4:7], v[224:227], v[18:33]
	v_exp_f32_e32 v96, v96
	v_exp_f32_e32 v97, v97
	v_cvt_pk_bf16_f32 v230, v94, v95
	v_cvt_pk_bf16_f32 v231, v96, v97
	ds_read_b64_tr_b16 v[4:5], v207 offset:27840
	ds_read_b64_tr_b16 v[6:7], v207 offset:30400
	s_waitcnt lgkmcnt(14)
	v_mfma_f32_32x32x16_bf16 v[66:81], v[240:243], v[228:231], v[66:81]
	v_exp_f32_e32 v98, v98
	v_exp_f32_e32 v99, v99
	v_add_f32_e32 v2, v2, v90
	v_add_f32_e32 v17, v17, v91
	ds_read_b64_tr_b16 v[240:241], v207 offset:32768
	ds_read_b64_tr_b16 v[242:243], v207 offset:35328
	s_waitcnt lgkmcnt(14)
	v_mfma_f32_32x32x16_bf16 v[50:65], v[244:247], v[228:231], v[50:65]
	v_exp_f32_e32 v100, v100
	v_exp_f32_e32 v101, v101
	v_cvt_pk_bf16_f32 v232, v98, v99
	v_add_f32_e32 v2, v2, v92
	v_add_f32_e32 v17, v17, v93
	ds_read_b64_tr_b16 v[244:245], v207 offset:32832
	ds_read_b64_tr_b16 v[246:247], v207 offset:35392
	s_waitcnt lgkmcnt(14)
	v_mfma_f32_32x32x16_bf16 v[34:49], v[248:251], v[228:231], v[34:49]
	v_exp_f32_e32 v102, v102
	v_exp_f32_e32 v103, v103
	v_cvt_pk_bf16_f32 v233, v100, v101
	v_add_f32_e32 v2, v2, v94
	v_add_f32_e32 v17, v17, v95
	ds_read_b64_tr_b16 v[248:249], v207 offset:32896
	ds_read_b64_tr_b16 v[250:251], v207 offset:35456
	s_waitcnt lgkmcnt(14)
	v_mfma_f32_32x32x16_bf16 v[18:33], v[252:255], v[228:231], v[18:33]
	v_exp_f32_e32 v104, v104
	v_exp_f32_e32 v105, v105
	v_cvt_pk_bf16_f32 v234, v102, v103
	v_cvt_pk_bf16_f32 v235, v104, v105
	v_add_f32_e32 v2, v2, v96
	v_add_f32_e32 v17, v17, v97
	ds_read_b64_tr_b16 v[252:253], v207 offset:32960
	ds_read_b64_tr_b16 v[254:255], v207 offset:35520
	s_waitcnt lgkmcnt(14)
	v_mfma_f32_32x32x16_bf16 v[66:81], v[12:15], v[232:235], v[66:81]
	s_mov_b64 s[58:59], 0
	v_exp_f32_e32 v106, v106
	v_exp_f32_e32 v107, v107
	v_add_f32_e32 v2, v2, v98
	v_add_f32_e32 v17, v17, v99
	s_waitcnt lgkmcnt(12)
	v_mfma_f32_32x32x16_bf16 v[50:65], v[8:11], v[232:235], v[50:65]
	v_exp_f32_e32 v108, v108
	v_exp_f32_e32 v109, v109
	v_cvt_pk_bf16_f32 v236, v106, v107
	v_add_f32_e32 v2, v2, v100
	v_add_f32_e32 v17, v17, v101
	s_waitcnt lgkmcnt(10)
	v_mfma_f32_32x32x16_bf16 v[34:49], v[162:165], v[232:235], v[34:49]
	v_exp_f32_e32 v110, v110
	v_exp_f32_e32 v111, v111
	v_cvt_pk_bf16_f32 v237, v108, v109
	v_add_f32_e32 v2, v2, v102
	v_add_f32_e32 v17, v17, v103
	s_waitcnt lgkmcnt(8)
	v_mfma_f32_32x32x16_bf16 v[18:33], v[4:7], v[232:235], v[18:33]
	v_exp_f32_e32 v112, v112
	v_exp_f32_e32 v113, v113
	v_cvt_pk_bf16_f32 v238, v110, v111
	v_cvt_pk_bf16_f32 v239, v112, v113
	v_add_f32_e32 v2, v2, v104
	v_add_f32_e32 v17, v17, v105
	s_waitcnt lgkmcnt(6)
	v_mfma_f32_32x32x16_bf16 v[66:81], v[240:243], v[236:239], v[66:81]
	v_add_f32_e32 v2, v2, v106
	v_add_f32_e32 v17, v17, v107
	s_waitcnt lgkmcnt(4)
	v_mfma_f32_32x32x16_bf16 v[50:65], v[244:247], v[236:239], v[50:65]
	v_add_f32_e32 v2, v2, v108
	v_add_f32_e32 v17, v17, v109
	s_waitcnt lgkmcnt(2)
	v_mfma_f32_32x32x16_bf16 v[34:49], v[248:251], v[236:239], v[34:49]
	v_add_f32_e32 v2, v2, v110
	v_add_f32_e32 v17, v17, v111
	s_waitcnt lgkmcnt(0)
	v_mfma_f32_32x32x16_bf16 v[18:33], v[252:255], v[236:239], v[18:33]
	v_add_f32_e32 v2, v2, v112
	v_add_f32_e32 v17, v17, v113
	v_add_f32_e32 v2, v2, v17
	v_add_f32_e32 v168, v168, v2

.LBB0_549:
	v_add_u32_e32 v16, v206, v205
	ds_read_b128 v[4:7], v16 offset:37888
	ds_read_b128 v[8:11], v16 offset:37920
	v_add_u32_e32 v2, s84, v220
	v_cvt_f32_i32_e32 v2, v2
	s_andn2_b64 vcc, exec, s[58:59]
	v_fma_f32 v2, v190, v2, -v185
	v_fma_f32 v82, 0, v190, v2
	v_add_f32_e32 v83, v190, v2
	v_pk_fma_f32 v[84:85], v[190:191], s[16:17], v[2:3] op_sel_hi:[1,1,0]
	v_pk_fma_f32 v[86:87], v[190:191], s[18:19], v[2:3] op_sel_hi:[1,1,0]
	v_pk_fma_f32 v[88:89], v[190:191], s[20:21], v[2:3] op_sel_hi:[1,1,0]
	v_pk_fma_f32 v[90:91], v[190:191], s[22:23], v[2:3] op_sel_hi:[1,1,0]
	v_pk_fma_f32 v[92:93], v[190:191], s[24:25], v[2:3] op_sel_hi:[1,1,0]
	v_pk_fma_f32 v[94:95], v[190:191], s[36:37], v[2:3] op_sel_hi:[1,1,0]
	v_pk_fma_f32 v[96:97], v[190:191], s[54:55], v[2:3] op_sel_hi:[1,1,0]
	v_add_f32_e32 v2, v219, v2
	v_fma_f32 v98, 0, v190, v2
	s_waitcnt lgkmcnt(1)
	v_mfma_f32_32x32x16_bf16 v[82:97], v[4:7], v[114:117], v[82:97]
	v_add_f32_e32 v99, v190, v2
	v_fma_f32 v100, v190, s16, v2
	v_fma_f32 v101, v191, s17, v2
	v_fma_f32 v102, v190, s18, v2
	v_fma_f32 v103, v191, s19, v2
	v_pk_fma_f32 v[104:105], v[190:191], s[20:21], v[2:3] op_sel_hi:[1,1,0]
	v_pk_fma_f32 v[106:107], v[190:191], s[22:23], v[2:3] op_sel_hi:[1,1,0]
	v_pk_fma_f32 v[108:109], v[190:191], s[24:25], v[2:3] op_sel_hi:[1,1,0]
	v_pk_fma_f32 v[110:111], v[190:191], s[36:37], v[2:3] op_sel_hi:[1,1,0]
	s_waitcnt lgkmcnt(0)
	v_mfma_f32_32x32x16_bf16 v[82:97], v[8:11], v[118:121], v[82:97]
	ds_read_b128 v[4:7], v16 offset:37952
	ds_read_b128 v[8:11], v16 offset:37984
	v_fma_f32 v112, v190, s54, v2
	v_fma_f32 v113, v191, s55, v2
	s_waitcnt lgkmcnt(1)
	v_mfma_f32_32x32x16_bf16 v[82:97], v[4:7], v[122:125], v[82:97]
	ds_read_b128 v[4:7], v16 offset:46592
	ds_read_b128 v[12:15], v16 offset:46624
	s_waitcnt lgkmcnt(1)
	v_mfma_f32_32x32x16_bf16 v[98:113], v[4:7], v[114:117], v[98:113]
	s_waitcnt lgkmcnt(0)
	v_mfma_f32_32x32x16_bf16 v[98:113], v[12:15], v[118:121], v[98:113]
	ds_read_b128 v[4:7], v16 offset:46656
	ds_read_b128 v[224:227], v16 offset:46688
	ds_read_b64_tr_b16 v[162:163], v210 offset:0
	ds_read_b64_tr_b16 v[164:165], v210 offset:2560
	ds_read_b64_tr_b16 v[12:13], v210 offset:64
	ds_read_b64_tr_b16 v[14:15], v210 offset:2624
	s_waitcnt lgkmcnt(5)
	v_mfma_f32_32x32x16_bf16 v[98:113], v[4:7], v[122:125], v[98:113]
	v_mfma_f32_32x32x16_bf16 v[82:97], v[8:11], v[126:129], v[82:97]
	ds_read_b64_tr_b16 v[8:9], v210 offset:128
	ds_read_b64_tr_b16 v[10:11], v210 offset:2688
	ds_read_b64_tr_b16 v[4:5], v210 offset:192
	ds_read_b64_tr_b16 v[6:7], v210 offset:2752
	s_waitcnt lgkmcnt(8)
	v_mfma_f32_32x32x16_bf16 v[98:113], v[224:227], v[126:129], v[98:113]
	s_cbranch_vccnz .LBB0_551
	v_add_u32_e32 v2, s84, v222
	v_add_u32_e32 v17, 0x7a0, v2
	v_add_u32_e32 v16, 0x780, v2
	v_cmp_le_i32_e32 vcc, v17, v184
	s_nop 6
	v_cndmask_b32_e32 v98, v217, v98, vcc
	v_cmp_lt_i32_e32 vcc, v16, v184
	s_nop 1
	v_cndmask_b32_e32 v83, v217, v83, vcc
	v_cmp_le_i32_e32 vcc, v16, v184
	v_add_u32_e32 v16, 0x7a1, v2
	s_nop 0
	v_cndmask_b32_e32 v82, v217, v82, vcc
	v_cmp_le_i32_e32 vcc, v16, v184
	v_add_u32_e32 v16, 0x782, v2
	s_nop 0
	v_cndmask_b32_e32 v99, v217, v99, vcc
	v_cmp_le_i32_e32 vcc, v16, v184
	v_add_u32_e32 v16, 0x7a2, v2
	s_nop 0
	v_cndmask_b32_e32 v84, v217, v84, vcc
	v_cmp_le_i32_e32 vcc, v16, v184
	v_add_u32_e32 v16, 0x783, v2
	s_nop 0
	v_cndmask_b32_e32 v100, v217, v100, vcc
	v_cmp_le_i32_e32 vcc, v16, v184
	v_add_u32_e32 v16, 0x7a3, v2
	s_nop 0
	v_cndmask_b32_e32 v85, v217, v85, vcc
	v_cmp_le_i32_e32 vcc, v16, v184
	v_add_u32_e32 v16, 0x788, v2
	s_nop 0
	v_cndmask_b32_e32 v101, v217, v101, vcc
	v_cmp_le_i32_e32 vcc, v16, v184
	v_add_u32_e32 v16, 0x7a8, v2
	s_nop 0
	v_cndmask_b32_e32 v86, v217, v86, vcc
	v_cmp_le_i32_e32 vcc, v16, v184
	v_add_u32_e32 v16, 0x789, v2
	s_nop 0
	v_cndmask_b32_e32 v102, v217, v102, vcc
	v_cmp_le_i32_e32 vcc, v16, v184
	v_add_u32_e32 v16, 0x7a9, v2
	s_nop 0
	v_cndmask_b32_e32 v87, v217, v87, vcc
	v_cmp_le_i32_e32 vcc, v16, v184
	v_add_u32_e32 v16, 0x78a, v2
	s_nop 0
	v_cndmask_b32_e32 v103, v217, v103, vcc
	v_cmp_le_i32_e32 vcc, v16, v184
	v_add_u32_e32 v16, 0x7aa, v2
	s_nop 0
	v_cndmask_b32_e32 v88, v217, v88, vcc
	v_cmp_le_i32_e32 vcc, v16, v184
	v_add_u32_e32 v16, 0x78b, v2
	s_nop 0
	v_cndmask_b32_e32 v104, v217, v104, vcc
	v_cmp_le_i32_e32 vcc, v16, v184
	v_add_u32_e32 v16, 0x7ab, v2
	s_nop 0
	v_cndmask_b32_e32 v89, v217, v89, vcc
	v_cmp_le_i32_e32 vcc, v16, v184
	v_add_u32_e32 v16, 0x790, v2
	s_nop 0
	v_cndmask_b32_e32 v105, v217, v105, vcc
	v_cmp_le_i32_e32 vcc, v16, v184
	v_add_u32_e32 v16, 0x7b0, v2
	s_nop 0
	v_cndmask_b32_e32 v90, v217, v90, vcc
	v_cmp_le_i32_e32 vcc, v16, v184
	v_add_u32_e32 v16, 0x791, v2
	s_nop 0
	v_cndmask_b32_e32 v106, v217, v106, vcc
	v_cmp_le_i32_e32 vcc, v16, v184
	v_add_u32_e32 v16, 0x7b1, v2
	s_nop 0
	v_cndmask_b32_e32 v91, v217, v91, vcc
	v_cmp_le_i32_e32 vcc, v16, v184
	v_add_u32_e32 v16, 0x792, v2
	s_nop 0
	v_cndmask_b32_e32 v107, v217, v107, vcc
	v_cmp_le_i32_e32 vcc, v16, v184
	v_add_u32_e32 v16, 0x7b2, v2
	s_nop 0
	v_cndmask_b32_e32 v92, v217, v92, vcc
	v_cmp_le_i32_e32 vcc, v16, v184
	v_add_u32_e32 v16, 0x793, v2
	s_nop 0
	v_cndmask_b32_e32 v108, v217, v108, vcc
	v_cmp_le_i32_e32 vcc, v16, v184
	v_add_u32_e32 v16, 0x7b3, v2
	s_nop 0
	v_cndmask_b32_e32 v93, v217, v93, vcc
	v_cmp_le_i32_e32 vcc, v16, v184
	v_add_u32_e32 v16, 0x798, v2
	s_nop 0
	v_cndmask_b32_e32 v109, v217, v109, vcc
	v_cmp_le_i32_e32 vcc, v16, v184
	v_add_u32_e32 v16, 0x7b8, v2
	s_nop 0
	v_cndmask_b32_e32 v94, v217, v94, vcc
	v_cmp_le_i32_e32 vcc, v16, v184
	v_add_u32_e32 v16, 0x799, v2
	s_nop 0
	v_cndmask_b32_e32 v110, v217, v110, vcc
	v_cmp_le_i32_e32 vcc, v16, v184
	v_add_u32_e32 v16, 0x7b9, v2
	s_nop 0
	v_cndmask_b32_e32 v95, v217, v95, vcc
	v_cmp_le_i32_e32 vcc, v16, v184
	v_add_u32_e32 v16, 0x79a, v2
	s_nop 0
	v_cndmask_b32_e32 v111, v217, v111, vcc
	v_cmp_le_i32_e32 vcc, v16, v184
	v_add_u32_e32 v16, 0x7ba, v2
	s_nop 0
	v_cndmask_b32_e32 v96, v217, v96, vcc
	v_cmp_le_i32_e32 vcc, v16, v184
	v_add_u32_e32 v16, 0x79b, v2
	v_add_u32_e32 v2, 0x7bb, v2
	v_cndmask_b32_e32 v112, v217, v112, vcc
	v_cmp_le_i32_e32 vcc, v16, v184
	s_nop 1
	v_cndmask_b32_e32 v97, v217, v97, vcc
	v_cmp_le_i32_e32 vcc, v2, v184
	s_nop 1
	v_cndmask_b32_e32 v113, v217, v113, vcc

.LBB0_556:
	s_nop 2
	v_exp_f32_e32 v82, v82
	v_exp_f32_e32 v83, v83
	v_exp_f32_e32 v84, v84
	v_exp_f32_e32 v85, v85
	ds_read_b64_tr_b16 v[240:241], v210 offset:5120
	ds_read_b64_tr_b16 v[242:243], v210 offset:7680
	ds_read_b64_tr_b16 v[244:245], v210 offset:5184
	ds_read_b64_tr_b16 v[246:247], v210 offset:7744
	ds_read_b64_tr_b16 v[248:249], v210 offset:5248
	ds_read_b64_tr_b16 v[250:251], v210 offset:7808
	ds_read_b64_tr_b16 v[252:253], v210 offset:5312
	ds_read_b64_tr_b16 v[254:255], v210 offset:7872
	v_exp_f32_e32 v86, v86
	v_exp_f32_e32 v87, v87
	v_exp_f32_e32 v88, v88
	v_exp_f32_e32 v89, v89
	v_cvt_pk_bf16_f32 v224, v82, v83
	v_cvt_pk_bf16_f32 v225, v84, v85
	v_cvt_pk_bf16_f32 v226, v86, v87
	v_cvt_pk_bf16_f32 v227, v88, v89
	s_waitcnt lgkmcnt(14)
	v_mfma_f32_32x32x16_bf16 v[66:81], v[162:165], v[224:227], v[66:81]
	v_exp_f32_e32 v90, v90
	v_exp_f32_e32 v91, v91
	v_add_f32_e32 v2, v82, v83
	v_add_f32_e32 v17, v84, v85
	ds_read_b64_tr_b16 v[162:163], v210 offset:10240
	ds_read_b64_tr_b16 v[164:165], v210 offset:12800
	s_waitcnt lgkmcnt(14)
	v_mfma_f32_32x32x16_bf16 v[50:65], v[12:15], v[224:227], v[50:65]
	v_exp_f32_e32 v92, v92
	v_exp_f32_e32 v93, v93
	v_cvt_pk_bf16_f32 v228, v90, v91
	v_add_f32_e32 v2, v2, v86
	v_add_f32_e32 v17, v17, v87
	ds_read_b64_tr_b16 v[12:13], v210 offset:10304
	ds_read_b64_tr_b16 v[14:15], v210 offset:12864
	s_waitcnt lgkmcnt(14)
	v_mfma_f32_32x32x16_bf16 v[34:49], v[8:11], v[224:227], v[34:49]
	v_exp_f32_e32 v94, v94
	v_exp_f32_e32 v95, v95
	v_cvt_pk_bf16_f32 v229, v92, v93
	v_add_f32_e32 v2, v2, v88
	v_add_f32_e32 v17, v17, v89
	ds_read_b64_tr_b16 v[8:9], v210 offset:10368
	ds_read_b64_tr_b16 v[10:11], v210 offset:12928
	s_waitcnt lgkmcnt(14)
	v_mfma_f32_32x32x16_bf16 v[18:33], v[4:7], v[224:227], v[18:33]
	v_exp_f32_e32 v96, v96
	v_exp_f32_e32 v97, v97
	v_cvt_pk_bf16_f32 v230, v94, v95
	v_cvt_pk_bf16_f32 v231, v96, v97
	ds_read_b64_tr_b16 v[4:5], v210 offset:10432
	ds_read_b64_tr_b16 v[6:7], v210 offset:12992
	s_waitcnt lgkmcnt(14)
	v_mfma_f32_32x32x16_bf16 v[66:81], v[240:243], v[228:231], v[66:81]
	v_exp_f32_e32 v98, v98
	v_exp_f32_e32 v99, v99
	v_add_f32_e32 v2, v2, v90
	v_add_f32_e32 v17, v17, v91
	ds_read_b64_tr_b16 v[240:241], v210 offset:15360
	ds_read_b64_tr_b16 v[242:243], v210 offset:17920
	s_waitcnt lgkmcnt(14)
	v_mfma_f32_32x32x16_bf16 v[50:65], v[244:247], v[228:231], v[50:65]
	v_exp_f32_e32 v100, v100
	v_exp_f32_e32 v101, v101
	v_cvt_pk_bf16_f32 v232, v98, v99
	v_add_f32_e32 v2, v2, v92
	v_add_f32_e32 v17, v17, v93
	ds_read_b64_tr_b16 v[244:245], v210 offset:15424
	ds_read_b64_tr_b16 v[246:247], v210 offset:17984
	s_waitcnt lgkmcnt(14)
	v_mfma_f32_32x32x16_bf16 v[34:49], v[248:251], v[228:231], v[34:49]
	v_exp_f32_e32 v102, v102
	v_exp_f32_e32 v103, v103
	v_cvt_pk_bf16_f32 v233, v100, v101
	v_add_f32_e32 v2, v2, v94
	v_add_f32_e32 v17, v17, v95
	ds_read_b64_tr_b16 v[248:249], v210 offset:15488
	ds_read_b64_tr_b16 v[250:251], v210 offset:18048
	s_waitcnt lgkmcnt(14)
	v_mfma_f32_32x32x16_bf16 v[18:33], v[252:255], v[228:231], v[18:33]
	v_exp_f32_e32 v104, v104
	v_exp_f32_e32 v105, v105
	v_cvt_pk_bf16_f32 v234, v102, v103
	v_cvt_pk_bf16_f32 v235, v104, v105
	v_add_f32_e32 v2, v2, v96
	v_add_f32_e32 v17, v17, v97
	ds_read_b64_tr_b16 v[252:253], v210 offset:15552
	ds_read_b64_tr_b16 v[254:255], v210 offset:18112
	s_waitcnt lgkmcnt(14)
	v_mfma_f32_32x32x16_bf16 v[66:81], v[162:165], v[232:235], v[66:81]
	s_mov_b64 s[58:59], 0
	v_exp_f32_e32 v106, v106
	v_exp_f32_e32 v107, v107
	v_add_f32_e32 v2, v2, v98
	v_add_f32_e32 v17, v17, v99
	s_waitcnt lgkmcnt(12)
	v_mfma_f32_32x32x16_bf16 v[50:65], v[12:15], v[232:235], v[50:65]
	v_exp_f32_e32 v108, v108
	v_exp_f32_e32 v109, v109
	v_cvt_pk_bf16_f32 v236, v106, v107
	v_add_f32_e32 v2, v2, v100
	v_add_f32_e32 v17, v17, v101
	s_waitcnt lgkmcnt(10)
	v_mfma_f32_32x32x16_bf16 v[34:49], v[8:11], v[232:235], v[34:49]
	v_exp_f32_e32 v110, v110
	v_exp_f32_e32 v111, v111
	v_cvt_pk_bf16_f32 v237, v108, v109
	v_add_f32_e32 v2, v2, v102
	v_add_f32_e32 v17, v17, v103
	s_waitcnt lgkmcnt(8)
	v_mfma_f32_32x32x16_bf16 v[18:33], v[4:7], v[232:235], v[18:33]
	v_exp_f32_e32 v112, v112
	v_exp_f32_e32 v113, v113
	v_cvt_pk_bf16_f32 v238, v110, v111
	v_cvt_pk_bf16_f32 v239, v112, v113
	v_add_f32_e32 v2, v2, v104
	v_add_f32_e32 v17, v17, v105
	s_waitcnt lgkmcnt(6)
	v_mfma_f32_32x32x16_bf16 v[66:81], v[240:243], v[236:239], v[66:81]
	v_add_f32_e32 v2, v2, v106
	v_add_f32_e32 v17, v17, v107
	s_waitcnt lgkmcnt(4)
	v_mfma_f32_32x32x16_bf16 v[50:65], v[244:247], v[236:239], v[50:65]
	v_add_f32_e32 v2, v2, v108
	v_add_f32_e32 v17, v17, v109
	s_waitcnt lgkmcnt(2)
	v_mfma_f32_32x32x16_bf16 v[34:49], v[248:251], v[236:239], v[34:49]
	v_add_f32_e32 v2, v2, v110
	v_add_f32_e32 v17, v17, v111
	s_waitcnt lgkmcnt(0)
	v_mfma_f32_32x32x16_bf16 v[18:33], v[252:255], v[236:239], v[18:33]
	v_add_f32_e32 v2, v2, v112
	v_add_f32_e32 v17, v17, v113
	v_add_f32_e32 v2, v2, v17
	v_add_f32_e32 v168, v168, v2
	s_cmp_ge_i32 s85, s81
	s_cbranch_scc1 .LBB0_548

.LBB0_563:
	s_and_saveexec_b64 s[4:5], s[26:27]
	s_cbranch_execz .LBB0_519
	v_mov_b32_e32 v2, s62
	s_waitcnt vmcnt(0)
	ds_write_b32 v2, v218
	s_branch .LBB0_519

	.amdhsa_kernel _Z8fwd_mega4Args
		.amdhsa_group_segment_fixed_size 0
		.amdhsa_private_segment_fixed_size 0
		.amdhsa_kernarg_size 456
		.amdhsa_user_sgpr_count 2
		.amdhsa_user_sgpr_dispatch_ptr 0
		.amdhsa_user_sgpr_queue_ptr 0
		.amdhsa_user_sgpr_kernarg_segment_ptr 1
		.amdhsa_user_sgpr_dispatch_id 0
		.amdhsa_user_sgpr_kernarg_preload_length 0
		.amdhsa_user_sgpr_kernarg_preload_offset 0
		.amdhsa_user_sgpr_private_segment_size 0
		.amdhsa_uses_dynamic_stack 0
		.amdhsa_enable_private_segment 0
		.amdhsa_system_sgpr_workgroup_id_x 1
		.amdhsa_system_sgpr_workgroup_id_y 0
		.amdhsa_system_sgpr_workgroup_id_z 0
		.amdhsa_system_sgpr_workgroup_info 0
		.amdhsa_system_vgpr_workitem_id 2
		.amdhsa_next_free_vgpr 256
		.amdhsa_next_free_sgpr 102
		.amdhsa_accum_offset 256
		.amdhsa_reserve_vcc 1
		.amdhsa_float_round_mode_32 0
		.amdhsa_float_round_mode_16_64 0
		.amdhsa_float_denorm_mode_32 3
		.amdhsa_float_denorm_mode_16_64 3
		.amdhsa_dx10_clamp 1
		.amdhsa_ieee_mode 1
		.amdhsa_fp16_overflow 0
		.amdhsa_tg_split 0
		.amdhsa_exception_fp_ieee_invalid_op 0
		.amdhsa_exception_fp_denorm_src 0
		.amdhsa_exception_fp_ieee_div_zero 0
		.amdhsa_exception_fp_ieee_overflow 0
		.amdhsa_exception_fp_ieee_underflow 0
		.amdhsa_exception_fp_ieee_inexact 0
		.amdhsa_exception_int_div_zero 0
	.end_amdhsa_kernel

amdhsa.kernels:
  - .agpr_count:     0
    .args:
      - .offset:         0
        .size:           200
        .value_kind:     by_value
      - .offset:         200
        .size:           4
        .value_kind:     hidden_block_count_x
      - .offset:         204
        .size:           4
        .value_kind:     hidden_block_count_y
      - .offset:         208
        .size:           4
        .value_kind:     hidden_block_count_z
      - .offset:         212
        .size:           2
        .value_kind:     hidden_group_size_x
      - .offset:         214
        .size:           2
        .value_kind:     hidden_group_size_y
      - .offset:         216
        .size:           2
        .value_kind:     hidden_group_size_z
      - .offset:         218
        .size:           2
        .value_kind:     hidden_remainder_x
      - .offset:         220
        .size:           2
        .value_kind:     hidden_remainder_y
      - .offset:         222
        .size:           2
        .value_kind:     hidden_remainder_z
      - .offset:         240
        .size:           8
        .value_kind:     hidden_global_offset_x
      - .offset:         248
        .size:           8
        .value_kind:     hidden_global_offset_y
      - .offset:         256
        .size:           8
        .value_kind:     hidden_global_offset_z
      - .offset:         264
        .size:           2
        .value_kind:     hidden_grid_dims
      - .offset:         288
        .size:           8
        .value_kind:     hidden_multigrid_sync_arg
      - .offset:         320
        .size:           4
        .value_kind:     hidden_dynamic_lds_size
    .group_segment_fixed_size: 0
    .kernarg_segment_align: 8
    .kernarg_segment_size: 456
    .language:       OpenCL C
    .language_version:
      - 2
      - 0
    .max_flat_workgroup_size: 512
    .name:           _Z8fwd_mega4Args
    .private_segment_fixed_size: 0
    .sgpr_count:     108
    .sgpr_spill_count: 0
    .symbol:         _Z8fwd_mega4Args.kd
    .uniform_work_group_size: 1
    .uses_dynamic_stack: false
    .vgpr_count:     256
    .vgpr_spill_count: 0
    .wavefront_size: 64
